# noS6 plus P14 moved to the tail of P12's barrier interval and P15 into P13's interval (EU relocated to d_out+256MiB), removing seams 14 and 15
# speedup vs baseline: 1.0018x; 1.0017x over previous
_Z8mega_fwd4Args:
	s_mov_b32 s98, 0
	s_mov_b32 s96, s2
	v_readfirstlane_b32 s2, v0
	s_lshr_b32 s2, s2, 6
	v_mbcnt_lo_u32_b32 v3, -1, 0
	v_mbcnt_hi_u32_b32 v3, -1, v3
	s_load_dword s15, s[0:1], 0xf8
	s_load_dwordx2 s[94:95], s[0:1], 0xe0
	s_load_dwordx4 s[4:7], s[0:1], 0xe8
	s_load_dwordx8 s[68:75], s[0:1], 0xc0
	v_writelane_b32 v254, s2, 0
	s_add_u32 s2, s0, 0xf8
	s_addc_u32 s3, s1, 0
	s_waitcnt lgkmcnt(0)
	v_writelane_b32 v254, s4, 1
	s_mov_b32 s10, s96
	s_nop 0
	v_writelane_b32 v254, s5, 2
	v_writelane_b32 v254, s6, 3
	v_writelane_b32 v254, s7, 4
	v_writelane_b32 v254, s2, 5
	s_nop 1
	v_writelane_b32 v254, s3, 6
	s_and_b32 s3, s15, 7
	s_mov_b32 s2, 0
	s_cmp_lg_u32 s3, 0
	s_cbranch_scc1 .LBB0_2
	s_ashr_i32 s4, s96, 31
	s_lshr_b32 s4, s4, 29
	s_add_i32 s4, s96, s4
	s_and_b32 s5, s4, -8
	s_ashr_i32 s3, s15, 3
	s_sub_i32 s5, s96, s5
	s_mul_i32 s3, s3, s5
	s_ashr_i32 s4, s4, 3
	s_add_i32 s10, s3, s4

.LBB0_934:
	s_cmp_eq_u32 s98, 0
	s_cbranch_scc0 .Lmy_norm_903
	v_writelane_b32 v255, s0, 10
	v_writelane_b32 v255, s1, 11
	v_writelane_b32 v255, s2, 12
	v_writelane_b32 v255, s3, 13
	v_writelane_b32 v255, s4, 14
	v_writelane_b32 v255, s5, 15
	v_writelane_b32 v255, s6, 16
	v_writelane_b32 v255, s7, 17
	v_writelane_b32 v255, s16, 18
	v_writelane_b32 v255, s17, 19
	v_writelane_b32 v255, s18, 20
	v_writelane_b32 v255, s19, 21
	v_writelane_b32 v255, s21, 22
	v_writelane_b32 v255, s23, 23
	v_writelane_b32 v255, s24, 24
	v_writelane_b32 v255, s25, 25
	v_writelane_b32 v255, s26, 26
	v_writelane_b32 v255, s27, 27
	v_writelane_b32 v255, s28, 28
	v_writelane_b32 v255, s29, 29
	v_writelane_b32 v255, s30, 30
	v_writelane_b32 v255, s31, 31
	v_writelane_b32 v255, s36, 32
	v_writelane_b32 v255, s37, 33
	v_writelane_b32 v255, s38, 34
	v_writelane_b32 v255, s40, 35
	v_writelane_b32 v255, s42, 36
	v_writelane_b32 v255, s43, 37
	v_writelane_b32 v255, s44, 38
	v_writelane_b32 v255, s45, 39
	v_writelane_b32 v255, s54, 40
	v_writelane_b32 v255, s64, 41
	s_mov_b64 s[0:1], -1
	s_branch .LBB0_1138

.LBB0_988:
	s_cmp_eq_u32 s98, 1
	s_cbranch_scc0 .Lmy_norm_988
	v_writelane_b32 v255, s0, 10
	v_writelane_b32 v255, s1, 11
	v_writelane_b32 v255, s2, 12
	v_writelane_b32 v255, s3, 13
	v_writelane_b32 v255, s4, 14
	v_writelane_b32 v255, s5, 15
	v_writelane_b32 v255, s6, 16
	v_writelane_b32 v255, s7, 17
	v_writelane_b32 v255, s16, 18
	v_writelane_b32 v255, s17, 19
	v_writelane_b32 v255, s18, 20
	s_mov_b64 s[0:1], -1
	s_branch .LBB0_1233

.LBB0_1138:
	v_readlane_b32 s4, v254, 1
	s_cmp_lt_i32 s4, 15
	v_readlane_b32 s5, v254, 2
	s_cselect_b64 s[2:3], -1, 0
	s_and_b64 s[4:5], s[2:3], s[0:1]
	s_andn2_b64 vcc, exec, s[4:5]
	v_readlane_b32 s6, v254, 3
	v_readlane_b32 s7, v254, 4
	s_cmp_lg_u32 s98, 0
	s_cbranch_scc1 .LBB0_1179
	s_cbranch_vccnz .LBB0_1179
	v_mbcnt_lo_u32_b32 v8, -1, 0
	v_mbcnt_hi_u32_b32 v8, -1, v8
	s_cmpk_lt_i32 s96, 0x800
	v_add_u32_e32 v224, s97, v8
	s_cselect_b64 s[0:1], -1, 0
	s_cmpk_gt_i32 s96, 0x7ff
	v_readfirstlane_b32 s18, v224
	s_cbranch_scc1 .LBB0_1145
	s_ashr_i32 s2, s96, 31
	s_lshr_b32 s2, s2, 29
	s_add_i32 s6, s96, s2
	s_and_b32 s2, s6, -8
	s_sub_i32 s7, s96, s2
	s_cmp_gt_i32 s7, -1
	s_cbranch_scc0 .LBB0_1142
	s_lshl_b32 s8, s7, 8
	s_cbranch_execz .LBB0_1143
	s_branch .LBB0_1144

.LBB0_1148:
	s_add_u32 s10, s74, 0x10000000
	s_addc_u32 s11, s75, 0
	s_add_u32 s12, s94, 0x25300000
	s_mov_b64 s[16:17], 0x80
	s_addc_u32 s13, s95, 0
	s_and_b32 s54, s0, 3
	s_add_i32 m0, s50, 0x18000
	v_lshl_add_u64 v[6:7], v[6:7], 0, s[16:17]
	s_lshl_b32 s0, s1, 13
	s_lshl_b32 s19, s54, 12
	s_waitcnt vmcnt(2)
	s_barrier
	global_load_lds_dwordx4 v[6:7], off
	v_lshl_add_u64 v[4:5], v[4:5], 0, s[16:17]
	s_add_i32 m0, s50, 0x1a000
	s_add_i32 s55, s50, 0x8000
	s_add_i32 s56, s50, 0xa000
	global_load_lds_dwordx4 v[4:5], off
	v_lshl_add_u64 v[0:1], v[0:1], 0, s[16:17]
	s_mov_b32 m0, s55
	s_add_u32 s2, s42, 0x10080
	global_load_lds_dwordx4 v[0:1], off
	v_lshl_add_u64 v[0:1], v[2:3], 0, s[16:17]
	s_mov_b32 m0, s56
	s_addc_u32 s3, s43, 0
	global_load_lds_dwordx4 v[0:1], off
	s_add_i32 m0, s50, 0x1c000
	v_lshl_add_u64 v[0:1], s[2:3], 0, v[130:131]
	global_load_lds_dwordx4 v[0:1], off
	v_lshl_add_u64 v[0:1], s[2:3], 0, v[134:135]
	s_add_i32 m0, s50, 0x1e000
	s_cmpk_lt_u32 s18, 0x100
	global_load_lds_dwordx4 v[0:1], off
	v_bfe_u32 v1, v8, 4, 2
	v_and_b32_e32 v0, 15, v8
	v_lshlrev_b32_e32 v3, 4, v1
	v_lshl_or_b32 v144, s1, 6, v0
	v_lshl_or_b32 v0, v0, 6, v3
	v_lshlrev_b32_e32 v3, 2, v8
	v_and_b32_e32 v3, 32, v3
	v_bitop3_b32 v145, v0, s19, v3 bitop3:0xde
	s_cselect_b64 s[18:19], -1, 0
	s_ashr_i32 s57, s15, 31
	s_ashr_i32 s2, s96, 31
	s_waitcnt vmcnt(6)
	s_add_u32 s20, s96, s15
	v_lshlrev_b32_e32 v2, 3, v1
	v_bitop3_b32 v4, v0, s0, v3 bitop3:0xde
	s_addc_u32 s21, s2, s57
	s_add_i32 s61, 0, 0x10000
	s_add_i32 s62, 0, 0x14000
	v_mbcnt_lo_u32_b32 v0, -1, 0
	v_lshl_or_b32 v146, s54, 5, v2
	v_cmp_eq_u32_e64 s[0:1], 0, v1
	v_mov_b64_e32 v[136:137], 0x800
	v_mov_b64_e32 v[138:139], 0x7ff
	v_add_u32_e32 v147, s61, v145
	v_add_u32_e32 v148, s62, v145
	v_add_u32_e32 v149, 0, v4
	s_mov_b64 s[22:23], 0x100
	s_mov_b64 s[24:25], 0x180
	v_mbcnt_hi_u32_b32 v150, -1, v0
	s_barrier
	s_waitcnt vmcnt(0)
	s_branch .LBB0_1151

.LBB0_1179:
	s_cmp_eq_u32 s98, 0
	s_cbranch_scc0 .Lmy_norm_1179
	s_mov_b32 s98, 1
	v_readlane_b32 s0, v255, 10
	v_readlane_b32 s1, v255, 11
	v_readlane_b32 s2, v255, 12
	v_readlane_b32 s3, v255, 13
	v_readlane_b32 s4, v255, 14
	v_readlane_b32 s5, v255, 15
	v_readlane_b32 s6, v255, 16
	v_readlane_b32 s7, v255, 17
	v_readlane_b32 s16, v255, 18
	v_readlane_b32 s17, v255, 19
	v_readlane_b32 s18, v255, 20
	v_readlane_b32 s19, v255, 21
	v_readlane_b32 s21, v255, 22
	v_readlane_b32 s23, v255, 23
	v_readlane_b32 s24, v255, 24
	v_readlane_b32 s25, v255, 25
	v_readlane_b32 s26, v255, 26
	v_readlane_b32 s27, v255, 27
	v_readlane_b32 s28, v255, 28
	v_readlane_b32 s29, v255, 29
	v_readlane_b32 s30, v255, 30
	v_readlane_b32 s31, v255, 31
	v_readlane_b32 s36, v255, 32
	v_readlane_b32 s37, v255, 33
	v_readlane_b32 s38, v255, 34
	v_readlane_b32 s40, v255, 35
	v_readlane_b32 s42, v255, 36
	v_readlane_b32 s43, v255, 37
	v_readlane_b32 s44, v255, 38
	v_readlane_b32 s45, v255, 39
	v_readlane_b32 s54, v255, 40
	v_readlane_b32 s64, v255, 41
	s_mov_b64 s[0:1], -1
	s_branch .LBB0_934
.Lmy_norm_1179:
	v_readlane_b32 s0, v254, 1
	v_readlane_b32 s1, v254, 2
	s_cmp_gt_i32 s1, 15
	v_readlane_b32 s2, v254, 3
	v_readlane_b32 s3, v254, 4
	s_cselect_b64 s[0:1], -1, 0
	s_and_b64 s[2:3], s[4:5], s[0:1]
	s_andn2_b64 vcc, exec, s[2:3]
	s_cmp_lg_u32 s98, 0
	s_cbranch_scc1 .LBB0_1233
	s_cbranch_vccnz .LBB0_1233
	s_waitcnt vmcnt(0)
	v_cmp_eq_u32_e32 vcc, 0, v224
	s_waitcnt vmcnt(0) lgkmcnt(0)
	s_barrier
	s_and_saveexec_b64 s[2:3], vcc
	s_cbranch_execz .LBB0_1232
	s_add_i32 s4, 0, 0x25820
	v_mov_b32_e32 v0, s4
	s_waitcnt vmcnt(0) expcnt(0) lgkmcnt(0)
	ds_read_b32 v2, v0
	s_add_i32 s4, 0, 0x25824
	v_mov_b32_e32 v0, s4
	ds_read_b32 v0, v0
	s_waitcnt lgkmcnt(1)
	v_cmp_ne_u32_e32 vcc, 0, v2
	s_cbranch_vccnz .LBB0_1196
	v_readlane_b32 s4, v254, 5
	v_readlane_b32 s5, v254, 6
	s_load_dwordx2 s[8:9], s[4:5], 0x4
	s_add_u32 s4, s82, 0x1000
	s_addc_u32 s5, s83, 0
	s_add_u32 s6, s82, 0x1100
	s_addc_u32 s7, s83, 0
	s_waitcnt lgkmcnt(0)
	s_mul_i32 s14, s8, s15
	s_add_u32 s8, s82, 0x1200
	s_mul_i32 s14, s14, s9
	s_addc_u32 s9, s83, 0
	s_add_u32 s10, s82, 0x1300
	s_addc_u32 s11, s83, 0
	s_mov_b32 s20, 1
	v_mov_b32_e32 v16, 0
	s_branch .LBB0_1184

.LBB0_1233:
	v_readlane_b32 s4, v254, 1
	s_cmp_lt_i32 s4, 16
	v_readlane_b32 s6, v254, 3
	v_readlane_b32 s7, v254, 4
	s_cselect_b64 s[2:3], -1, 0
	s_and_b64 s[6:7], s[2:3], s[0:1]
	v_readlane_b32 s0, v254, 52
	v_readlane_b32 s1, v254, 53
	s_andn2_b64 vcc, exec, s[6:7]
	v_readlane_b32 s5, v254, 2
	v_cndmask_b32_e64 v0, 0, 1, s[0:1]
	v_cmp_ne_u32_e64 s[0:1], 1, v0
	s_cmp_eq_u32 s98, 2
	s_cbranch_scc1 .LBB0_1239
	s_cbranch_vccnz .LBB0_1239
	v_mbcnt_lo_u32_b32 v0, -1, 0
	v_mbcnt_hi_u32_b32 v0, -1, v0
	s_and_b64 vcc, exec, s[0:1]
	v_add_u32_e32 v224, s97, v0
	s_cbranch_vccnz .LBB0_1239
	v_mbcnt_lo_u32_b32 v2, -1, 0
	v_readlane_b32 s16, v254, 54
	v_mbcnt_hi_u32_b32 v7, -1, v2
	v_readlane_b32 s17, v254, 55
	v_and_b32_e32 v2, 64, v7
	s_lshl_b64 s[4:5], s[16:17], 2
	v_add_u32_e32 v8, 64, v2
	v_xor_b32_e32 v2, 1, v7
	s_add_u32 s4, s94, s4
	v_cmp_lt_i32_e32 vcc, v2, v8
	v_xor_b32_e32 v3, 2, v7
	s_addc_u32 s5, s95, s5
	v_cndmask_b32_e32 v2, v7, v2, vcc
	v_cmp_lt_i32_e32 vcc, v3, v8
	v_xor_b32_e32 v4, 4, v7
	s_add_u32 s8, s4, 0x25b00000
	v_cndmask_b32_e32 v3, v7, v3, vcc
	v_cmp_lt_i32_e32 vcc, v4, v8
	v_xor_b32_e32 v5, 8, v7
	s_addc_u32 s9, s5, 0
	s_ashr_i32 s81, s80, 31
	v_cndmask_b32_e32 v4, v7, v4, vcc
	v_cmp_lt_i32_e32 vcc, v5, v8
	v_xor_b32_e32 v6, 16, v7
	s_lshl_b64 s[10:11], s[80:81], 2
	s_lshl_b64 s[4:5], s[16:17], 8
	v_cndmask_b32_e32 v5, v7, v5, vcc
	v_cmp_lt_i32_e32 vcc, v6, v8
	v_xor_b32_e32 v9, 32, v7
	s_add_u32 s4, s94, s4
	s_waitcnt lgkmcnt(0)
	v_ashrrev_i32_e32 v1, 31, v0
	v_cndmask_b32_e32 v6, v7, v6, vcc
	v_cmp_lt_i32_e32 vcc, v9, v8
	s_addc_u32 s5, s95, s5
	v_cmp_eq_u32_e64 s[2:3], 0, v0
	v_cndmask_b32_e32 v7, v7, v9, vcc
	v_lshl_add_u64 v[0:1], v[0:1], 2, s[4:5]
	s_mov_b64 s[4:5], 0x25300000
	v_lshlrev_b32_e32 v2, 2, v2
	v_lshlrev_b32_e32 v3, 2, v3
	v_lshlrev_b32_e32 v4, 2, v4
	v_lshlrev_b32_e32 v5, 2, v5
	v_lshlrev_b32_e32 v6, 2, v6
	v_lshlrev_b32_e32 v7, 2, v7
	v_lshl_add_u64 v[0:1], v[0:1], 0, s[4:5]
	s_lshl_b64 s[12:13], s[80:81], 8
	v_mov_b32_e32 v8, 0x358637bd
	s_mov_b32 s14, 0xf800000
	v_mov_b32_e32 v9, 0x260
	v_mov_b32_e32 v10, 0
	s_mov_b32 s18, s16
	s_branch .LBB0_1237

.LBB0_1239:
	s_cmp_eq_u32 s98, 1
	s_cbranch_scc0 .Lmy_norm_1239
	s_mov_b32 s98, 2
	v_readlane_b32 s0, v255, 10
	v_readlane_b32 s1, v255, 11
	v_readlane_b32 s2, v255, 12
	v_readlane_b32 s3, v255, 13
	v_readlane_b32 s4, v255, 14
	v_readlane_b32 s5, v255, 15
	v_readlane_b32 s6, v255, 16
	v_readlane_b32 s7, v255, 17
	v_readlane_b32 s16, v255, 18
	v_readlane_b32 s17, v255, 19
	v_readlane_b32 s18, v255, 20
	s_mov_b64 s[0:1], -1
	s_branch .LBB0_988
.Lmy_norm_1239:
	v_readlane_b32 s8, v254, 1
	v_readlane_b32 s9, v254, 2
	s_cmp_gt_i32 s9, 16
	s_cselect_b64 s[2:3], -1, 0
	s_and_b64 s[4:5], s[6:7], s[2:3]
	s_andn2_b64 vcc, exec, s[4:5]
	v_readlane_b32 s10, v254, 3
	v_readlane_b32 s11, v254, 4
	s_cmp_eq_u32 s98, 2
	s_cbranch_scc1 .LBB0_1293
	s_cbranch_vccnz .LBB0_1293
	s_waitcnt vmcnt(0)
	v_cmp_eq_u32_e32 vcc, 0, v224
	s_waitcnt vmcnt(0) lgkmcnt(0)
	s_barrier
	s_and_saveexec_b64 s[4:5], vcc
	s_cbranch_execz .LBB0_1292
	s_add_i32 s6, 0, 0x25820
	v_mov_b32_e32 v0, s6
	s_waitcnt vmcnt(0) expcnt(0) lgkmcnt(0)
	ds_read_b32 v2, v0
	s_add_i32 s6, 0, 0x25824
	v_mov_b32_e32 v0, s6
	ds_read_b32 v0, v0
	s_waitcnt lgkmcnt(1)
	v_cmp_ne_u32_e32 vcc, 0, v2
	s_cbranch_vccnz .LBB0_1256
	v_readlane_b32 s6, v254, 5
	v_readlane_b32 s7, v254, 6
	s_load_dwordx2 s[10:11], s[6:7], 0x4
	s_add_u32 s6, s82, 0x1000
	s_addc_u32 s7, s83, 0
	s_add_u32 s8, s82, 0x1100
	s_addc_u32 s9, s83, 0
	s_waitcnt lgkmcnt(0)
	s_mul_i32 s14, s10, s15
	s_add_u32 s10, s82, 0x1200
	s_mul_i32 s14, s14, s11
	s_addc_u32 s11, s83, 0
	s_add_u32 s12, s82, 0x1300
	s_addc_u32 s13, s83, 0
	s_mov_b32 s22, 1
	v_mov_b32_e32 v16, 0
	s_branch .LBB0_1244

.LBB0_1303:
	s_add_u32 s12, s94, 0x3bc00000
	s_addc_u32 s13, s95, 0
	s_add_u32 s16, s74, 0x10000000
	s_addc_u32 s17, s75, 0
	s_add_u32 s18, s94, 0x25b00000
	s_addc_u32 s19, s95, 0
	s_add_u32 s20, s94, 0x25300000
	s_mov_b64 s[22:23], 0x80
	s_addc_u32 s21, s95, 0
	s_and_b32 s51, s2, 3
	s_add_i32 m0, s47, 0x18000
	v_lshl_add_u64 v[6:7], v[6:7], 0, s[22:23]
	s_lshl_b32 s2, s3, 13
	s_lshl_b32 s24, s51, 12
	s_waitcnt vmcnt(2)
	s_barrier
	global_load_lds_dwordx4 v[6:7], off
	v_lshl_add_u64 v[4:5], v[4:5], 0, s[22:23]
	s_add_i32 m0, s47, 0x1a000
	s_add_i32 s52, s47, 0x8000
	s_add_i32 s53, s47, 0xa000
	global_load_lds_dwordx4 v[4:5], off
	v_lshl_add_u64 v[0:1], v[0:1], 0, s[22:23]
	s_mov_b32 m0, s52
	s_add_u32 s4, s42, 0x100080
	global_load_lds_dwordx4 v[0:1], off
	v_lshl_add_u64 v[0:1], v[2:3], 0, s[22:23]
	s_mov_b32 m0, s53
	s_addc_u32 s5, s43, 0
	global_load_lds_dwordx4 v[0:1], off
	s_add_i32 m0, s47, 0x1c000
	v_lshl_add_u64 v[0:1], s[4:5], 0, v[138:139]
	global_load_lds_dwordx4 v[0:1], off
	v_lshl_add_u64 v[0:1], s[4:5], 0, v[142:143]
	s_add_i32 m0, s47, 0x1e000
	s_cmpk_lt_u32 s14, 0x100
	global_load_lds_dwordx4 v[0:1], off
	v_bfe_u32 v1, v8, 4, 2
	v_and_b32_e32 v0, 15, v8
	v_lshlrev_b32_e32 v3, 4, v1
	s_waitcnt vmcnt(0)
	v_lshl_or_b32 v160, s3, 6, v0
	v_lshl_or_b32 v0, v0, 6, v3
	v_lshlrev_b32_e32 v3, 2, v8
	v_and_b32_e32 v3, 32, v3
	v_bitop3_b32 v4, v0, s2, v3 bitop3:0xde
	v_bitop3_b32 v161, v0, s24, v3 bitop3:0xde
	v_lshlrev_b32_e32 v0, 16, v9
	v_and_b32_e32 v0, 0xfffe0000, v0
	v_lshlrev_b32_e32 v2, 3, v1
	v_cmp_eq_u32_e64 s[2:3], 0, v1
	v_lshl_add_u32 v0, v10, 13, v0
	v_and_b32_e32 v1, 1, v9
	v_lshl_or_b32 v0, v1, 6, v0
	v_lshl_add_u32 v144, v11, 1, v0
	v_lshlrev_b32_e32 v0, 16, v12
	v_and_b32_e32 v0, 0xfffe0000, v0
	v_lshl_add_u32 v0, v13, 13, v0
	v_and_b32_e32 v1, 1, v12
	s_waitcnt vmcnt(6)
	v_lshl_or_b32 v0, v1, 6, v0
	s_cselect_b64 s[24:25], -1, 0
	v_lshl_add_u32 v146, v14, 1, v0
	s_add_i32 s56, 0, 0x10000
	s_add_i32 s57, 0, 0x14000
	v_mbcnt_lo_u32_b32 v0, -1, 0
	v_lshl_or_b32 v162, s51, 5, v2
	s_ashr_i32 s54, s15, 31
	s_ashr_i32 s55, s96, 31
	v_mov_b32_e32 v145, v139
	v_mov_b32_e32 v147, v139
	v_mov_b64_e32 v[148:149], 0x800
	v_mov_b64_e32 v[150:151], 0x7ff
	v_add_u32_e32 v163, s56, v161
	v_add_u32_e32 v164, s57, v161
	v_add_u32_e32 v165, 0, v4
	v_mbcnt_hi_u32_b32 v166, -1, v0
	s_mov_b32 s59, 0
	s_barrier
	s_branch .LBB0_1306

	.amdhsa_kernel _Z8mega_fwd4Args
		.amdhsa_group_segment_fixed_size 0
		.amdhsa_private_segment_fixed_size 0
		.amdhsa_kernarg_size 504
		.amdhsa_user_sgpr_count 2
		.amdhsa_user_sgpr_dispatch_ptr 0
		.amdhsa_user_sgpr_queue_ptr 0
		.amdhsa_user_sgpr_kernarg_segment_ptr 1
		.amdhsa_user_sgpr_dispatch_id 0
		.amdhsa_user_sgpr_kernarg_preload_length 0
		.amdhsa_user_sgpr_kernarg_preload_offset 0
		.amdhsa_user_sgpr_private_segment_size 0
		.amdhsa_uses_dynamic_stack 0
		.amdhsa_enable_private_segment 0
		.amdhsa_system_sgpr_workgroup_id_x 1
		.amdhsa_system_sgpr_workgroup_id_y 0
		.amdhsa_system_sgpr_workgroup_id_z 0
		.amdhsa_system_sgpr_workgroup_info 0
		.amdhsa_system_vgpr_workitem_id 0
		.amdhsa_next_free_vgpr 256
		.amdhsa_next_free_sgpr 99
		.amdhsa_accum_offset 256
		.amdhsa_reserve_vcc 1
		.amdhsa_float_round_mode_32 0
		.amdhsa_float_round_mode_16_64 0
		.amdhsa_float_denorm_mode_32 3
		.amdhsa_float_denorm_mode_16_64 3
		.amdhsa_dx10_clamp 1
		.amdhsa_ieee_mode 1
		.amdhsa_fp16_overflow 0
		.amdhsa_tg_split 0
		.amdhsa_exception_fp_ieee_invalid_op 0
		.amdhsa_exception_fp_denorm_src 0
		.amdhsa_exception_fp_ieee_div_zero 0
		.amdhsa_exception_fp_ieee_overflow 0
		.amdhsa_exception_fp_ieee_underflow 0
		.amdhsa_exception_fp_ieee_inexact 0
		.amdhsa_exception_int_div_zero 0
	.end_amdhsa_kernel

amdhsa.kernels:
  - .agpr_count:     0
    .args:
      - .offset:         0
        .size:           248
        .value_kind:     by_value
      - .offset:         248
        .size:           4
        .value_kind:     hidden_block_count_x
      - .offset:         252
        .size:           4
        .value_kind:     hidden_block_count_y
      - .offset:         256
        .size:           4
        .value_kind:     hidden_block_count_z
      - .offset:         260
        .size:           2
        .value_kind:     hidden_group_size_x
      - .offset:         262
        .size:           2
        .value_kind:     hidden_group_size_y
      - .offset:         264
        .size:           2
        .value_kind:     hidden_group_size_z
      - .offset:         266
        .size:           2
        .value_kind:     hidden_remainder_x
      - .offset:         268
        .size:           2
        .value_kind:     hidden_remainder_y
      - .offset:         270
        .size:           2
        .value_kind:     hidden_remainder_z
      - .offset:         288
        .size:           8
        .value_kind:     hidden_global_offset_x
      - .offset:         296
        .size:           8
        .value_kind:     hidden_global_offset_y
      - .offset:         304
        .size:           8
        .value_kind:     hidden_global_offset_z
      - .offset:         312
        .size:           2
        .value_kind:     hidden_grid_dims
      - .offset:         368
        .size:           4
        .value_kind:     hidden_dynamic_lds_size
    .group_segment_fixed_size: 0
    .kernarg_segment_align: 8
    .kernarg_segment_size: 504
    .language:       OpenCL C
    .language_version:
      - 2
      - 0
    .max_flat_workgroup_size: 512
    .name:           _Z8mega_fwd4Args
    .private_segment_fixed_size: 0
    .sgpr_count:     105
    .sgpr_spill_count: 87
    .symbol:         _Z8mega_fwd4Args.kd
    .uniform_work_group_size: 1
    .uses_dynamic_stack: false
    .vgpr_count:     256
    .vgpr_spill_count: 0
    .wavefront_size: 64
